# XCD-group-local barrier at row-local GEMM seams (FFN up/down, out-proj to FFN): 16 of 32 grid barriers skip cross-XCD phase
# speedup vs baseline: 1.0260x; 1.0062x over previous
; #define LAS __attribute__((address_space(3)))
; __device__ __forceinline__ unsigned xb_add(unsigned* p, unsigned v) { return __hip_atomic_fetch_add(p, v, __ATOMIC_RELAXED, __HIP_MEMORY_SCOPE_AGENT); }
; __device__ __forceinline__ unsigned xb_xcc_id() { return (unsigned)__builtin_amdgcn_s_getreg((3 << 11) | 20) & 0xFu; }
; __device__ __forceinline__ XcdBarrier xcd_barrier_post(unsigned* bar, volatile LAS unsigned* st) {
;     XcdBarrier b; b.bar = bar; b.x = xb_xcc_id(); b.st = st;
;     if (threadIdx.x == 0) (void)xb_add(&bar[XB_XCNT(b.x)], 1u);
;     return b;
; }
; __global__ void __launch_bounds__(NTHR, 2) fwd_kernel(Args a) {
;     ...
;     (void)xcd_barrier_post((unsigned*)(KWS + WS_CTL), (volatile LAS unsigned*)(lds + LDS_MISC));
.LBB0_179:
	s_or_b64 exec, exec, s[4:5]
	s_barrier
	s_load_dwordx2 s[4:5], s[58:59], 0xb8
	s_waitcnt lgkmcnt(0)
	s_getreg_b32 s2, hwreg(HW_REG_XCC_ID, 0, 4)
	s_mov_b32 s79, 0
	v_cmp_eq_u32_e64 s[62:63], 0, v228
	s_and_saveexec_b64 s[0:1], s[62:63]
	s_cbranch_execz .LBB0_182
	s_mov_b64 s[6:7], exec
	v_mbcnt_lo_u32_b32 v0, s6, 0
	v_mbcnt_hi_u32_b32 v0, s7, v0
	v_cmp_eq_u32_e32 vcc, 0, v0
	s_and_b64 s[8:9], exec, vcc
	s_mov_b64 exec, s[8:9]
	s_cbranch_execz .LBB0_182
	s_and_b32 s3, s2, 15
	s_and_b32 s8, s92, 7
	s_lshl_b32 s8, s8, 2
	s_add_i32 s8, s8, 0x9783580
	s_cmp_lg_u32 s76, 0x100
	s_cselect_b32 s9, 0xff, 0
	s_max_u32 s9, s9, s3
	v_mov_b32_e32 v0, s8
	v_mov_b32_e32 v1, s9
	global_atomic_umax v0, v1, s[4:5]
	s_sub_i32 s3, 15, s3
	v_mov_b32_e32 v1, s3
	global_atomic_umax v0, v1, s[4:5] offset:32
	s_waitcnt vmcnt(0)
	s_lshl_b32 s2, s2, 8
	s_and_b32 s2, s2, 0xf00
	s_add_u32 s2, s4, s2
	s_addc_u32 s3, s5, 0
	s_bcnt1_i32_b64 s4, s[6:7]
	v_mov_b32_e32 v0, 0x9780000
	v_mov_b32_e32 v1, s4
	global_atomic_add v0, v1, s[2:3] offset:1024

; __device__ __forceinline__ unsigned xb_ld(unsigned* p)              { return __hip_atomic_load(p, __ATOMIC_RELAXED, __HIP_MEMORY_SCOPE_AGENT); }
; __device__ __forceinline__ unsigned xb_add(unsigned* p, unsigned v) { return __hip_atomic_fetch_add(p, v, __ATOMIC_RELAXED, __HIP_MEMORY_SCOPE_AGENT); }
; #define XB_SPIN(cond, bar) do { unsigned _sp = 0; while (cond) { __builtin_amdgcn_s_sleep(1); \
;     if ((++_sp & 255u) == 0u) { if (xb_ld(&(bar)[XB_TMO])) break; if (_sp > XB_SPIN_CAP) { atomicAdd(&(bar)[XB_TMO], 1u); break; } } } } while (0)
; __device__ __forceinline__ void xcd_barrier(const XcdBarrier& b) {
;     asm volatile("s_waitcnt vmcnt(0)" ::: "memory");
;     __syncthreads();
;     if (threadIdx.x == 0) {
;         unsigned* bar = b.bar;
;         __builtin_amdgcn_s_waitcnt(0);
;         unsigned nloc = b.st[0], nx = b.st[1];
;         if (nloc == 0u) { xcd_barrier_complete(bar, b.x, nloc, nx); b.st[0] = nloc; b.st[1] = nx; }
;         const unsigned old = xb_add(&bar[XB_XSUB(b.x)], 1u);
;         const unsigned gen = old / nloc;
;         if (old + 1u == (gen + 1u) * nloc) {
;             __builtin_amdgcn_fence(__ATOMIC_RELEASE, "agent");
;             asm volatile("s_waitcnt vmcnt(0)" ::: "memory");
;             const unsigned og = xb_add(&bar[XB_TOP], 1u);
;             const unsigned tg = og / nx;
;             if (og + 1u == (tg + 1u) * nx) xb_add(&bar[XB_TOPGEN], 1u);
;             else XB_SPIN(xb_ld(&bar[XB_TOPGEN]) == tg, bar);
;             __builtin_amdgcn_fence(__ATOMIC_ACQUIRE, "agent");
;             xb_add(&bar[XB_XGEN(b.x)], 1u);
;             asm volatile("s_waitcnt vmcnt(0)" ::: "memory");
;         } else {
;             XB_SPIN(xb_ld(&bar[XB_XGEN(b.x)]) == gen, bar);
;             __builtin_amdgcn_fence(__ATOMIC_ACQUIRE, "agent");
;             asm volatile("s_waitcnt vmcnt(0)" ::: "memory");
;         }
;     }
.LBB0_207:
	s_load_dwordx2 s[6:7], s[58:59], 0xb8
	s_waitcnt lgkmcnt(0)
	s_getreg_b32 s2, hwreg(HW_REG_XCC_ID, 0, 4)
	s_waitcnt vmcnt(0)
	s_barrier
	s_and_saveexec_b64 s[4:5], s[62:63]
	s_xor_b64 s[4:5], exec, s[4:5]
	s_cbranch_execz .LBB0_260
	v_mov_b32_e32 v0, 0x21000
	ds_read_b32 v1, v0
	ds_read_b32 v2, v0 offset:8
	s_waitcnt lgkmcnt(0)
	v_readfirstlane_b32 s10, v1
	v_readfirstlane_b32 s11, v2
	s_cmp_eq_u32 s10, 0
	s_cbranch_scc1 .Lxbo_1
	s_cmp_lg_u32 s11, 0
	s_cbranch_scc1 .Lxbf_1
	v_mov_b32_e32 v16, 0x9783580
	global_load_dwordx4 v[0:3], v16, s[6:7] sc1
	global_load_dwordx4 v[4:7], v16, s[6:7] offset:16 sc1
	global_load_dwordx4 v[8:11], v16, s[6:7] offset:32 sc1
	global_load_dwordx4 v[12:15], v16, s[6:7] offset:48 sc1
	s_waitcnt vmcnt(0)
	v_add_u32_e32 v0, v0, v8
	v_add_u32_e32 v1, v1, v9
	v_add_u32_e32 v2, v2, v10
	v_add_u32_e32 v3, v3, v11
	v_add_u32_e32 v4, v4, v12
	v_add_u32_e32 v5, v5, v13
	v_add_u32_e32 v6, v6, v14
	v_add_u32_e32 v7, v7, v15
	v_xor_b32_e32 v0, 15, v0
	v_xor_b32_e32 v1, 15, v1
	v_xor_b32_e32 v2, 15, v2
	v_xor_b32_e32 v3, 15, v3
	v_xor_b32_e32 v4, 15, v4
	v_xor_b32_e32 v5, 15, v5
	v_xor_b32_e32 v6, 15, v6
	v_xor_b32_e32 v7, 15, v7
	v_or3_b32 v1, v1, v2, v3
	v_or3_b32 v4, v4, v5, v6
	v_or3_b32 v1, v1, v4, v7
	v_or_b32_e32 v1, v1, v0
	s_nop 0
	v_readfirstlane_b32 s11, v1
	s_cmp_eq_u32 s11, 0
	s_cselect_b32 s11, 1, 2
	v_mov_b32_e32 v2, s11
	v_mov_b32_e32 v0, 0x21000
	ds_write_b32 v0, v2 offset:8
	s_waitcnt lgkmcnt(0)
.Lxbf_1:
	s_cmp_eq_u32 s11, 1
	s_cbranch_scc0 .Lxbo_1
	s_and_b32 s12, s92, 7
	s_lshl_b32 s12, s12, 8
	s_add_i32 s13, s12, 0x9781480
	s_add_i32 s14, s12, 0x9782480
	v_mov_b32_e32 v1, s13
	v_mov_b32_e32 v2, 1
	global_atomic_add v3, v1, v2, s[6:7] sc0
	s_waitcnt vmcnt(0)
	v_readfirstlane_b32 s15, v3
	s_lshr_b32 s16, s15, 5
	s_add_i32 s15, s15, 1
	s_and_b32 s17, s15, 31
	v_mov_b32_e32 v1, s14
	s_cmp_lg_u32 s17, 0
	s_cbranch_scc1 .Lxbw_1
	global_atomic_add v1, v2, s[6:7]
	s_branch .Lxbd_1
.Lxbw_1:
	s_mov_b32 s18, 0
.Lxbs_1:
	s_sleep 1
	global_load_dword v3, v1, s[6:7] sc1
	s_waitcnt vmcnt(0)
	v_readfirstlane_b32 s17, v3
	s_cmp_lg_u32 s17, s16
	s_cbranch_scc1 .Lxbd_1
	s_add_i32 s18, s18, 1
	s_cmp_lt_u32 s18, 0x100000
	s_cbranch_scc1 .Lxbs_1
.Lxbd_1:
	s_waitcnt vmcnt(0)
	buffer_inv sc1
	s_waitcnt vmcnt(0)
	s_branch .LBB0_260
.Lxbo_1:
	v_readlane_b32 s10, v254, 31
	s_waitcnt vmcnt(0) expcnt(0) lgkmcnt(0)
	s_and_b32 s2, s2, 15
	v_mov_b32_e32 v0, s10
	ds_read_b32 v2, v0
	v_readlane_b32 s10, v254, 32
	s_waitcnt lgkmcnt(0)
	v_cmp_ne_u32_e32 vcc, 0, v2
	v_mov_b32_e32 v0, s10
	ds_read_b32 v0, v0
	s_cbranch_vccnz .LBB0_223
	s_add_u32 s10, s6, 0x9780200
	s_addc_u32 s11, s7, 0
	s_add_u32 s12, s6, 0x9780400
	s_addc_u32 s13, s7, 0
	s_add_u32 s14, s6, 0x9780500
	s_addc_u32 s15, s7, 0
	s_add_u32 s16, s6, 0x9780600
	s_addc_u32 s17, s7, 0
	s_add_u32 s18, s6, 0x9780700
	s_addc_u32 s19, s7, 0
	s_add_u32 s20, s6, 0x9780800
	s_addc_u32 s21, s7, 0
	s_add_u32 s22, s6, 0x9780900
	s_addc_u32 s23, s7, 0
	s_add_u32 s24, s6, 0x9780a00
	s_addc_u32 s25, s7, 0
	s_add_u32 s26, s6, 0x9780b00
	s_addc_u32 s27, s7, 0
	s_add_u32 s28, s6, 0x9780c00
	s_addc_u32 s29, s7, 0
	s_add_u32 s30, s6, 0x9780d00
	s_addc_u32 s31, s7, 0
	s_add_u32 s34, s6, 0x9780e00
	s_addc_u32 s35, s7, 0
	s_add_u32 s36, s6, 0x9780f00
	s_addc_u32 s37, s7, 0
	s_add_u32 s38, s6, 0x9781000
	s_addc_u32 s39, s7, 0
	s_add_u32 s40, s6, 0x9781100
	s_addc_u32 s41, s7, 0
	s_add_u32 s42, s6, 0x9781200
	s_addc_u32 s43, s7, 0
	s_add_u32 s44, s6, 0x9781300
	s_addc_u32 s45, s7, 0
	s_mov_b32 s54, 1
	s_branch .LBB0_211

; __device__ __forceinline__ unsigned xb_ld(unsigned* p)              { return __hip_atomic_load(p, __ATOMIC_RELAXED, __HIP_MEMORY_SCOPE_AGENT); }
; __device__ __forceinline__ unsigned xb_add(unsigned* p, unsigned v) { return __hip_atomic_fetch_add(p, v, __ATOMIC_RELAXED, __HIP_MEMORY_SCOPE_AGENT); }
; #define XB_SPIN(cond, bar) do { unsigned _sp = 0; while (cond) { __builtin_amdgcn_s_sleep(1); \
;     if ((++_sp & 255u) == 0u) { if (xb_ld(&(bar)[XB_TMO])) break; if (_sp > XB_SPIN_CAP) { atomicAdd(&(bar)[XB_TMO], 1u); break; } } } } while (0)
; __device__ __forceinline__ void xcd_barrier(const XcdBarrier& b) {
;     asm volatile("s_waitcnt vmcnt(0)" ::: "memory");
;     __syncthreads();
;     if (threadIdx.x == 0) {
;         unsigned* bar = b.bar;
;         __builtin_amdgcn_s_waitcnt(0);
;         unsigned nloc = b.st[0], nx = b.st[1];
;         if (nloc == 0u) { xcd_barrier_complete(bar, b.x, nloc, nx); b.st[0] = nloc; b.st[1] = nx; }
;         const unsigned old = xb_add(&bar[XB_XSUB(b.x)], 1u);
;         const unsigned gen = old / nloc;
;         if (old + 1u == (gen + 1u) * nloc) {
;             __builtin_amdgcn_fence(__ATOMIC_RELEASE, "agent");
;             asm volatile("s_waitcnt vmcnt(0)" ::: "memory");
;             const unsigned og = xb_add(&bar[XB_TOP], 1u);
;             const unsigned tg = og / nx;
;             if (og + 1u == (tg + 1u) * nx) xb_add(&bar[XB_TOPGEN], 1u);
;             else XB_SPIN(xb_ld(&bar[XB_TOPGEN]) == tg, bar);
;             __builtin_amdgcn_fence(__ATOMIC_ACQUIRE, "agent");
;             xb_add(&bar[XB_XGEN(b.x)], 1u);
;             asm volatile("s_waitcnt vmcnt(0)" ::: "memory");
;         } else {
;             XB_SPIN(xb_ld(&bar[XB_XGEN(b.x)]) == gen, bar);
;             __builtin_amdgcn_fence(__ATOMIC_ACQUIRE, "agent");
;             asm volatile("s_waitcnt vmcnt(0)" ::: "memory");
;         }
;     }
.LBB0_334:
	s_load_dwordx2 s[6:7], s[58:59], 0xb8
	s_waitcnt lgkmcnt(0)
	s_getreg_b32 s2, hwreg(HW_REG_XCC_ID, 0, 4)
	s_waitcnt vmcnt(0)
	s_barrier
	s_and_saveexec_b64 s[4:5], s[62:63]
	s_xor_b64 s[4:5], exec, s[4:5]
	s_cbranch_execz .LBB0_387
	v_mov_b32_e32 v0, 0x21000
	ds_read_b32 v1, v0
	ds_read_b32 v2, v0 offset:8
	s_waitcnt lgkmcnt(0)
	v_readfirstlane_b32 s10, v1
	v_readfirstlane_b32 s11, v2
	s_cmp_eq_u32 s10, 0
	s_cbranch_scc1 .Lxbo_2
	v_readlane_b32 s12, v255, 4
	s_cmp_eq_u32 s12, 2
	s_cbranch_scc0 .Lxbo_2
	s_cmp_lg_u32 s11, 0
	s_cbranch_scc1 .Lxbf_2
	v_mov_b32_e32 v16, 0x9783580
	global_load_dwordx4 v[0:3], v16, s[6:7] sc1
	global_load_dwordx4 v[4:7], v16, s[6:7] offset:16 sc1
	global_load_dwordx4 v[8:11], v16, s[6:7] offset:32 sc1
	global_load_dwordx4 v[12:15], v16, s[6:7] offset:48 sc1
	s_waitcnt vmcnt(0)
	v_add_u32_e32 v0, v0, v8
	v_add_u32_e32 v1, v1, v9
	v_add_u32_e32 v2, v2, v10
	v_add_u32_e32 v3, v3, v11
	v_add_u32_e32 v4, v4, v12
	v_add_u32_e32 v5, v5, v13
	v_add_u32_e32 v6, v6, v14
	v_add_u32_e32 v7, v7, v15
	v_xor_b32_e32 v0, 15, v0
	v_xor_b32_e32 v1, 15, v1
	v_xor_b32_e32 v2, 15, v2
	v_xor_b32_e32 v3, 15, v3
	v_xor_b32_e32 v4, 15, v4
	v_xor_b32_e32 v5, 15, v5
	v_xor_b32_e32 v6, 15, v6
	v_xor_b32_e32 v7, 15, v7
	v_or3_b32 v1, v1, v2, v3
	v_or3_b32 v4, v4, v5, v6
	v_or3_b32 v1, v1, v4, v7
	v_or_b32_e32 v1, v1, v0
	s_nop 0
	v_readfirstlane_b32 s11, v1
	s_cmp_eq_u32 s11, 0
	s_cselect_b32 s11, 1, 2
	v_mov_b32_e32 v2, s11
	v_mov_b32_e32 v0, 0x21000
	ds_write_b32 v0, v2 offset:8
	s_waitcnt lgkmcnt(0)

; __device__ __forceinline__ unsigned xb_ld(unsigned* p)              { return __hip_atomic_load(p, __ATOMIC_RELAXED, __HIP_MEMORY_SCOPE_AGENT); }
; __device__ __forceinline__ unsigned xb_add(unsigned* p, unsigned v) { return __hip_atomic_fetch_add(p, v, __ATOMIC_RELAXED, __HIP_MEMORY_SCOPE_AGENT); }
; #define XB_SPIN(cond, bar) do { unsigned _sp = 0; while (cond) { __builtin_amdgcn_s_sleep(1); \
;     if ((++_sp & 255u) == 0u) { if (xb_ld(&(bar)[XB_TMO])) break; if (_sp > XB_SPIN_CAP) { atomicAdd(&(bar)[XB_TMO], 1u); break; } } } } while (0)
; __device__ __forceinline__ void xcd_barrier(const XcdBarrier& b) {
;     asm volatile("s_waitcnt vmcnt(0)" ::: "memory");
;     __syncthreads();
;     if (threadIdx.x == 0) {
;         unsigned* bar = b.bar;
;         __builtin_amdgcn_s_waitcnt(0);
;         unsigned nloc = b.st[0], nx = b.st[1];
;         if (nloc == 0u) { xcd_barrier_complete(bar, b.x, nloc, nx); b.st[0] = nloc; b.st[1] = nx; }
;         const unsigned old = xb_add(&bar[XB_XSUB(b.x)], 1u);
;         const unsigned gen = old / nloc;
;         if (old + 1u == (gen + 1u) * nloc) {
;             __builtin_amdgcn_fence(__ATOMIC_RELEASE, "agent");
;             asm volatile("s_waitcnt vmcnt(0)" ::: "memory");
;             const unsigned og = xb_add(&bar[XB_TOP], 1u);
;             const unsigned tg = og / nx;
;             if (og + 1u == (tg + 1u) * nx) xb_add(&bar[XB_TOPGEN], 1u);
;             else XB_SPIN(xb_ld(&bar[XB_TOPGEN]) == tg, bar);
;             __builtin_amdgcn_fence(__ATOMIC_ACQUIRE, "agent");
;             xb_add(&bar[XB_XGEN(b.x)], 1u);
;             asm volatile("s_waitcnt vmcnt(0)" ::: "memory");
;         } else {
;             XB_SPIN(xb_ld(&bar[XB_XGEN(b.x)]) == gen, bar);
;             __builtin_amdgcn_fence(__ATOMIC_ACQUIRE, "agent");
;             asm volatile("s_waitcnt vmcnt(0)" ::: "memory");
;         }
;     }
.Lxbo_2:
	v_readlane_b32 s8, v254, 31
	s_waitcnt vmcnt(0) expcnt(0) lgkmcnt(0)
	s_and_b32 s2, s2, 15
	v_mov_b32_e32 v0, s8
	ds_read_b32 v2, v0
	v_readlane_b32 s8, v254, 32
	s_waitcnt lgkmcnt(0)
	v_cmp_ne_u32_e32 vcc, 0, v2
	v_mov_b32_e32 v0, s8
	ds_read_b32 v0, v0
	s_cbranch_vccnz .LBB0_350
	s_add_u32 s8, s6, 0x9780200
	s_addc_u32 s9, s7, 0
	s_add_u32 s10, s6, 0x9780400
	s_addc_u32 s11, s7, 0
	s_add_u32 s12, s6, 0x9780500
	s_addc_u32 s13, s7, 0
	s_add_u32 s14, s6, 0x9780600
	s_addc_u32 s15, s7, 0
	s_add_u32 s16, s6, 0x9780700
	s_addc_u32 s17, s7, 0
	s_add_u32 s18, s6, 0x9780800
	s_addc_u32 s19, s7, 0
	s_add_u32 s20, s6, 0x9780900
	s_addc_u32 s21, s7, 0
	s_add_u32 s22, s6, 0x9780a00
	s_addc_u32 s23, s7, 0
	s_add_u32 s24, s6, 0x9780b00
	s_addc_u32 s25, s7, 0
	s_add_u32 s26, s6, 0x9780c00
	s_addc_u32 s27, s7, 0
	s_add_u32 s28, s6, 0x9780d00
	s_addc_u32 s29, s7, 0
	s_add_u32 s30, s6, 0x9780e00
	s_addc_u32 s31, s7, 0
	s_add_u32 s34, s6, 0x9780f00
	s_addc_u32 s35, s7, 0
	s_add_u32 s36, s6, 0x9781000
	s_addc_u32 s37, s7, 0
	s_add_u32 s38, s6, 0x9781100
	s_addc_u32 s39, s7, 0
	s_add_u32 s40, s6, 0x9781200
	s_addc_u32 s41, s7, 0
	s_add_u32 s42, s6, 0x9781300
	s_addc_u32 s43, s7, 0
	s_mov_b32 s50, 1
	s_branch .LBB0_338

; __device__ __forceinline__ unsigned xb_ld(unsigned* p)              { return __hip_atomic_load(p, __ATOMIC_RELAXED, __HIP_MEMORY_SCOPE_AGENT); }
; __device__ __forceinline__ unsigned xb_add(unsigned* p, unsigned v) { return __hip_atomic_fetch_add(p, v, __ATOMIC_RELAXED, __HIP_MEMORY_SCOPE_AGENT); }
; #define XB_SPIN(cond, bar) do { unsigned _sp = 0; while (cond) { __builtin_amdgcn_s_sleep(1); \
;     if ((++_sp & 255u) == 0u) { if (xb_ld(&(bar)[XB_TMO])) break; if (_sp > XB_SPIN_CAP) { atomicAdd(&(bar)[XB_TMO], 1u); break; } } } } while (0)
; __device__ __forceinline__ void xcd_barrier(const XcdBarrier& b) {
;     asm volatile("s_waitcnt vmcnt(0)" ::: "memory");
;     __syncthreads();
;     if (threadIdx.x == 0) {
;         unsigned* bar = b.bar;
;         __builtin_amdgcn_s_waitcnt(0);
;         unsigned nloc = b.st[0], nx = b.st[1];
;         if (nloc == 0u) { xcd_barrier_complete(bar, b.x, nloc, nx); b.st[0] = nloc; b.st[1] = nx; }
;         const unsigned old = xb_add(&bar[XB_XSUB(b.x)], 1u);
;         const unsigned gen = old / nloc;
;         if (old + 1u == (gen + 1u) * nloc) {
;             __builtin_amdgcn_fence(__ATOMIC_RELEASE, "agent");
;             asm volatile("s_waitcnt vmcnt(0)" ::: "memory");
;             const unsigned og = xb_add(&bar[XB_TOP], 1u);
;             const unsigned tg = og / nx;
;             if (og + 1u == (tg + 1u) * nx) xb_add(&bar[XB_TOPGEN], 1u);
;             else XB_SPIN(xb_ld(&bar[XB_TOPGEN]) == tg, bar);
;             __builtin_amdgcn_fence(__ATOMIC_ACQUIRE, "agent");
;             xb_add(&bar[XB_XGEN(b.x)], 1u);
;             asm volatile("s_waitcnt vmcnt(0)" ::: "memory");
;         } else {
;             XB_SPIN(xb_ld(&bar[XB_XGEN(b.x)]) == gen, bar);
;             __builtin_amdgcn_fence(__ATOMIC_ACQUIRE, "agent");
;             asm volatile("s_waitcnt vmcnt(0)" ::: "memory");
;         }
;     }
.Lxb4_join:
	s_getpc_b64 s[98:99]

; __device__ __forceinline__ unsigned xb_ld(unsigned* p)              { return __hip_atomic_load(p, __ATOMIC_RELAXED, __HIP_MEMORY_SCOPE_AGENT); }
; __device__ __forceinline__ unsigned xb_add(unsigned* p, unsigned v) { return __hip_atomic_fetch_add(p, v, __ATOMIC_RELAXED, __HIP_MEMORY_SCOPE_AGENT); }
; #define XB_SPIN(cond, bar) do { unsigned _sp = 0; while (cond) { __builtin_amdgcn_s_sleep(1); \
;     if ((++_sp & 255u) == 0u) { if (xb_ld(&(bar)[XB_TMO])) break; if (_sp > XB_SPIN_CAP) { atomicAdd(&(bar)[XB_TMO], 1u); break; } } } } while (0)
; __device__ __forceinline__ void xcd_barrier(const XcdBarrier& b) {
;     asm volatile("s_waitcnt vmcnt(0)" ::: "memory");
;     __syncthreads();
;     if (threadIdx.x == 0) {
;         unsigned* bar = b.bar;
;         __builtin_amdgcn_s_waitcnt(0);
;         unsigned nloc = b.st[0], nx = b.st[1];
;         if (nloc == 0u) { xcd_barrier_complete(bar, b.x, nloc, nx); b.st[0] = nloc; b.st[1] = nx; }
;         const unsigned old = xb_add(&bar[XB_XSUB(b.x)], 1u);
;         const unsigned gen = old / nloc;
;         if (old + 1u == (gen + 1u) * nloc) {
;             __builtin_amdgcn_fence(__ATOMIC_RELEASE, "agent");
;             asm volatile("s_waitcnt vmcnt(0)" ::: "memory");
;             const unsigned og = xb_add(&bar[XB_TOP], 1u);
;             const unsigned tg = og / nx;
;             if (og + 1u == (tg + 1u) * nx) xb_add(&bar[XB_TOPGEN], 1u);
;             else XB_SPIN(xb_ld(&bar[XB_TOPGEN]) == tg, bar);
;             __builtin_amdgcn_fence(__ATOMIC_ACQUIRE, "agent");
;             xb_add(&bar[XB_XGEN(b.x)], 1u);
;             asm volatile("s_waitcnt vmcnt(0)" ::: "memory");
;         } else {
;             XB_SPIN(xb_ld(&bar[XB_XGEN(b.x)]) == gen, bar);
;             __builtin_amdgcn_fence(__ATOMIC_ACQUIRE, "agent");
;             asm volatile("s_waitcnt vmcnt(0)" ::: "memory");
;         }
;     }
.LBB0_1211:
	v_mov_b32_e32 v0, 0x21000
	ds_read_b32 v1, v0
	ds_read_b32 v2, v0 offset:8
	s_waitcnt lgkmcnt(0)
	v_readfirstlane_b32 s10, v1
	v_readfirstlane_b32 s11, v2
	s_cmp_eq_u32 s10, 0
	s_cbranch_scc1 .Lxbo_4
	s_cmp_lg_u32 s11, 0
	s_cbranch_scc1 .Lxbf_4
	v_mov_b32_e32 v16, 0x9783580
	global_load_dwordx4 v[0:3], v16, s[4:5] sc1
	global_load_dwordx4 v[4:7], v16, s[4:5] offset:16 sc1
	global_load_dwordx4 v[8:11], v16, s[4:5] offset:32 sc1
	global_load_dwordx4 v[12:15], v16, s[4:5] offset:48 sc1
	s_waitcnt vmcnt(0)
	v_add_u32_e32 v0, v0, v8
	v_add_u32_e32 v1, v1, v9
	v_add_u32_e32 v2, v2, v10
	v_add_u32_e32 v3, v3, v11
	v_add_u32_e32 v4, v4, v12
	v_add_u32_e32 v5, v5, v13
	v_add_u32_e32 v6, v6, v14
	v_add_u32_e32 v7, v7, v15
	v_xor_b32_e32 v0, 15, v0
	v_xor_b32_e32 v1, 15, v1
	v_xor_b32_e32 v2, 15, v2
	v_xor_b32_e32 v3, 15, v3
	v_xor_b32_e32 v4, 15, v4
	v_xor_b32_e32 v5, 15, v5
	v_xor_b32_e32 v6, 15, v6
	v_xor_b32_e32 v7, 15, v7
	v_or3_b32 v1, v1, v2, v3
	v_or3_b32 v4, v4, v5, v6
	v_or3_b32 v1, v1, v4, v7
	v_or_b32_e32 v1, v1, v0
	s_nop 0
	v_readfirstlane_b32 s11, v1
	s_cmp_eq_u32 s11, 0
	s_cselect_b32 s11, 1, 2
	v_mov_b32_e32 v2, s11
	v_mov_b32_e32 v0, 0x21000
	ds_write_b32 v0, v2 offset:8
	s_waitcnt lgkmcnt(0)
.Lxbf_4:
	s_cmp_eq_u32 s11, 1
	s_cbranch_scc0 .Lxbo_4
	s_and_b32 s12, s92, 7
	s_lshl_b32 s12, s12, 8
	s_add_i32 s13, s12, 0x9781480
	s_add_i32 s14, s12, 0x9782480
	v_mov_b32_e32 v1, s13
	v_mov_b32_e32 v2, 1
	global_atomic_add v3, v1, v2, s[4:5] sc0
	s_waitcnt vmcnt(0)
	v_readfirstlane_b32 s15, v3
	s_lshr_b32 s16, s15, 5
	s_add_i32 s15, s15, 1
	s_and_b32 s17, s15, 31
	v_mov_b32_e32 v1, s14
	s_cmp_lg_u32 s17, 0
	s_cbranch_scc1 .Lxbw_4
	global_atomic_add v1, v2, s[4:5]
	s_branch .Lxbd_4

; __device__ __forceinline__ unsigned xb_ld(unsigned* p)              { return __hip_atomic_load(p, __ATOMIC_RELAXED, __HIP_MEMORY_SCOPE_AGENT); }
; #define XB_SPIN(cond, bar) do { unsigned _sp = 0; while (cond) { __builtin_amdgcn_s_sleep(1); \
;     if ((++_sp & 255u) == 0u) { if (xb_ld(&(bar)[XB_TMO])) break; if (_sp > XB_SPIN_CAP) { atomicAdd(&(bar)[XB_TMO], 1u); break; } } } } while (0)
; __device__ __forceinline__ void xcd_barrier(const XcdBarrier& b) {
;     ...
;             XB_SPIN(xb_ld(&bar[XB_XGEN(b.x)]) == gen, bar);
.Lxbs_4:
	s_sleep 1
	global_load_dword v3, v1, s[4:5] sc1
	s_waitcnt vmcnt(0)
	v_readfirstlane_b32 s17, v3
	s_cmp_lg_u32 s17, s16
	s_cbranch_scc1 .Lxbd_4
	s_add_i32 s18, s18, 1
	s_cmp_lt_u32 s18, 0x100000
	s_cbranch_scc1 .Lxbs_4
